# pipelined GEMM K-loops: two DMA pieces right after the stage barrier, then two per MFMA group starting with the first group (the schedule no longer skips the first group)
# speedup vs baseline: 1.0078x; 1.0037x over previous
; template <int EPI, int MI>
; DI void gemm_tile(const GemmDesc& g, int tm, int tn, char* smem) {
;     ...
;   const int rowA = wm * (32 * MI) + r, rowB = wn * 64 + r;
;   const int hk = hh ^ ((r & 7) ^ ((r >> 3) & 3));
;     ...
;   G_GLDS(0, 0);
;   asm volatile("s_waitcnt vmcnt(0)" ::: "memory");
;   __syncthreads();
;   for (int kt = 0; kt < nk; kt += 2) {
;     if (kt + 1 < nk) G_GLDS(kt + 1, 1);
;     G_COMPUTE(0);
;     asm volatile("s_waitcnt vmcnt(0)" ::: "memory");
;     __syncthreads();
;     if (kt + 1 < nk) {
;       if (kt + 2 < nk) G_GLDS(kt + 2, 0);
;       G_COMPUTE(1);
;       asm volatile("s_waitcnt vmcnt(0)" ::: "memory");
;       __syncthreads();
;     }
;   }
.Lga_loop:
	ds_read_b128 v[232:235], v162 offset:8192
	s_waitcnt lgkmcnt(2)
	v_mfma_f32_32x32x16_bf16 v[80:95], v[224:227], v[236:239], v[80:95]
	v_mfma_f32_32x32x16_bf16 v[64:79], v[224:227], v[240:243], v[64:79]
	s_add_u32 m0, s100, 0x8000
	v_lshl_add_u64 v[106:107], v[174:175], 0, s[24:25]
	global_load_lds_dwordx4 v[106:107], off
	s_add_u32 m0, s100, 0x9000
	v_lshl_add_u64 v[106:107], v[174:175], 0, s[26:27]
	global_load_lds_dwordx4 v[106:107], off
	ds_read_b128 v[244:247], v167 offset:49152
	ds_read_b128 v[248:251], v167 offset:53248
	ds_read_b128 v[224:227], v163
	s_waitcnt lgkmcnt(4)
	v_mfma_f32_32x32x16_bf16 v[48:63], v[228:231], v[236:239], v[48:63]
	v_mfma_f32_32x32x16_bf16 v[32:47], v[228:231], v[240:243], v[32:47]
	s_add_u32 m0, s100, 0xa000
	v_lshl_add_u64 v[106:107], v[174:175], 0, s[28:29]
	global_load_lds_dwordx4 v[106:107], off
	s_add_u32 m0, s100, 0xb000
	v_lshl_add_u64 v[106:107], v[174:175], 0, s[30:31]
	global_load_lds_dwordx4 v[106:107], off
	v_lshl_add_u64 v[174:175], v[174:175], 0, s[18:19]
	ds_read_b128 v[228:231], v163 offset:4096
	s_waitcnt lgkmcnt(4)
	v_mfma_f32_32x32x16_bf16 v[16:31], v[232:235], v[236:239], v[16:31]
	v_mfma_f32_32x32x16_bf16 v[0:15], v[232:235], v[240:243], v[0:15]
	s_add_u32 m0, s100, 0x10000
	v_lshl_add_u64 v[106:107], v[176:177], 0, s[18:19]
	global_load_lds_dwordx4 v[106:107], off
	s_add_u32 m0, s100, 0x11000
	v_lshl_add_u64 v[106:107], v[176:177], 0, s[42:43]
	global_load_lds_dwordx4 v[106:107], off
	ds_read_b128 v[232:235], v163 offset:8192
	s_waitcnt lgkmcnt(2)
	v_mfma_f32_32x32x16_bf16 v[80:95], v[224:227], v[244:247], v[80:95]
	v_mfma_f32_32x32x16_bf16 v[64:79], v[224:227], v[248:251], v[64:79]
	s_mov_b64 s[16:17], 0x20080
	s_add_u32 m0, s100, 0x12000
	v_lshl_add_u64 v[106:107], v[176:177], 0, s[16:17]
	global_load_lds_dwordx4 v[106:107], off
	s_mov_b64 s[16:17], 0x30080
	s_add_u32 m0, s100, 0x13000
	v_lshl_add_u64 v[106:107], v[176:177], 0, s[16:17]
	global_load_lds_dwordx4 v[106:107], off
	v_lshl_add_u64 v[176:177], v[176:177], 0, s[18:19]
	ds_read_b128 v[236:239], v168 offset:49152
	ds_read_b128 v[240:243], v168 offset:53248
	ds_read_b128 v[224:227], v164
	s_waitcnt lgkmcnt(4)
	v_mfma_f32_32x32x16_bf16 v[48:63], v[228:231], v[244:247], v[48:63]
	v_mfma_f32_32x32x16_bf16 v[32:47], v[228:231], v[248:251], v[32:47]
	ds_read_b128 v[228:231], v164 offset:4096
	s_waitcnt lgkmcnt(4)
	v_mfma_f32_32x32x16_bf16 v[16:31], v[232:235], v[244:247], v[16:31]
	v_mfma_f32_32x32x16_bf16 v[0:15], v[232:235], v[248:251], v[0:15]
	ds_read_b128 v[232:235], v164 offset:8192
	s_waitcnt lgkmcnt(2)
	v_mfma_f32_32x32x16_bf16 v[80:95], v[224:227], v[236:239], v[80:95]
	v_mfma_f32_32x32x16_bf16 v[64:79], v[224:227], v[240:243], v[64:79]
	ds_read_b128 v[244:247], v169 offset:49152
	ds_read_b128 v[248:251], v169 offset:53248
	ds_read_b128 v[224:227], v165
	s_waitcnt lgkmcnt(4)
	v_mfma_f32_32x32x16_bf16 v[48:63], v[228:231], v[236:239], v[48:63]
	v_mfma_f32_32x32x16_bf16 v[32:47], v[228:231], v[240:243], v[32:47]
	ds_read_b128 v[228:231], v165 offset:4096
	s_waitcnt lgkmcnt(4)
	v_mfma_f32_32x32x16_bf16 v[16:31], v[232:235], v[236:239], v[16:31]
	v_mfma_f32_32x32x16_bf16 v[0:15], v[232:235], v[240:243], v[0:15]
	ds_read_b128 v[232:235], v165 offset:8192
	s_waitcnt lgkmcnt(2)
	v_mfma_f32_32x32x16_bf16 v[80:95], v[224:227], v[244:247], v[80:95]
	v_mfma_f32_32x32x16_bf16 v[64:79], v[224:227], v[248:251], v[64:79]
	s_waitcnt lgkmcnt(0)
	s_waitcnt vmcnt(0)
	s_barrier
	s_cmp_eq_u32 s15, 14
	s_cbranch_scc1 .Lga_noearly
	s_mov_b32 m0, s100
	v_lshl_add_u64 v[106:107], v[174:175], 0, s[96:97]
	global_load_lds_dwordx4 v[106:107], off
	s_add_u32 m0, s100, 0x1000
	v_lshl_add_u64 v[106:107], v[174:175], 0, s[50:51]
	global_load_lds_dwordx4 v[106:107], off
; template <int EPI, int MI>
; DI void gemm_tile(const GemmDesc& g, int tm, int tn, char* smem) {
;     ...
;   const int rowA = wm * (32 * MI) + r, rowB = wn * 64 + r;
;   const int hk = hh ^ ((r & 7) ^ ((r >> 3) & 3));
;     ...
;   G_GLDS(0, 0);
;   asm volatile("s_waitcnt vmcnt(0)" ::: "memory");
;   __syncthreads();
;   for (int kt = 0; kt < nk; kt += 2) {
;     if (kt + 1 < nk) G_GLDS(kt + 1, 1);
;     G_COMPUTE(0);
;     asm volatile("s_waitcnt vmcnt(0)" ::: "memory");
;     __syncthreads();
;     if (kt + 1 < nk) {
;       if (kt + 2 < nk) G_GLDS(kt + 2, 0);
;       G_COMPUTE(1);
;       asm volatile("s_waitcnt vmcnt(0)" ::: "memory");
;       __syncthreads();
;     }
;   }
.Lga_noearly:
	ds_read_b128 v[236:239], v170
	ds_read_b128 v[240:243], v170 offset:4096
	ds_read_b128 v[224:227], v162 offset:24576
	v_mfma_f32_32x32x16_bf16 v[48:63], v[228:231], v[244:247], v[48:63]
	v_mfma_f32_32x32x16_bf16 v[32:47], v[228:231], v[248:251], v[32:47]
	ds_read_b128 v[228:231], v162 offset:28672
	v_mfma_f32_32x32x16_bf16 v[16:31], v[232:235], v[244:247], v[16:31]
	v_mfma_f32_32x32x16_bf16 v[0:15], v[232:235], v[248:251], v[0:15]
	s_cmp_eq_u32 s15, 14
	s_cbranch_scc1 .Lga_last
	ds_read_b128 v[232:235], v162 offset:32768
	s_waitcnt lgkmcnt(2)
	v_mfma_f32_32x32x16_bf16 v[80:95], v[224:227], v[236:239], v[80:95]
	v_mfma_f32_32x32x16_bf16 v[64:79], v[224:227], v[240:243], v[64:79]
	s_add_u32 m0, s100, 0x2000
	v_lshl_add_u64 v[106:107], v[174:175], 0, s[24:25]
	global_load_lds_dwordx4 v[106:107], off
	s_add_u32 m0, s100, 0x3000
	v_lshl_add_u64 v[106:107], v[174:175], 0, s[26:27]
	global_load_lds_dwordx4 v[106:107], off
	ds_read_b128 v[244:247], v171
	ds_read_b128 v[248:251], v171 offset:4096
	ds_read_b128 v[224:227], v163 offset:24576
	s_waitcnt lgkmcnt(4)
	v_mfma_f32_32x32x16_bf16 v[48:63], v[228:231], v[236:239], v[48:63]
	v_mfma_f32_32x32x16_bf16 v[32:47], v[228:231], v[240:243], v[32:47]
	s_add_u32 m0, s100, 0x4000
	v_lshl_add_u64 v[106:107], v[174:175], 0, s[28:29]
	global_load_lds_dwordx4 v[106:107], off
	s_add_u32 m0, s100, 0x5000
	v_lshl_add_u64 v[106:107], v[174:175], 0, s[30:31]
	global_load_lds_dwordx4 v[106:107], off
	v_lshl_add_u64 v[174:175], v[174:175], 0, s[18:19]
	ds_read_b128 v[228:231], v163 offset:28672
	s_waitcnt lgkmcnt(4)
	v_mfma_f32_32x32x16_bf16 v[16:31], v[232:235], v[236:239], v[16:31]
	v_mfma_f32_32x32x16_bf16 v[0:15], v[232:235], v[240:243], v[0:15]
	s_add_u32 m0, s100, 0xc000
	v_lshl_add_u64 v[106:107], v[176:177], 0, s[18:19]
	global_load_lds_dwordx4 v[106:107], off
	s_add_u32 m0, s100, 0xd000
	v_lshl_add_u64 v[106:107], v[176:177], 0, s[42:43]
	global_load_lds_dwordx4 v[106:107], off
	ds_read_b128 v[232:235], v163 offset:32768
	s_waitcnt lgkmcnt(2)
	v_mfma_f32_32x32x16_bf16 v[80:95], v[224:227], v[244:247], v[80:95]
	v_mfma_f32_32x32x16_bf16 v[64:79], v[224:227], v[248:251], v[64:79]
	s_mov_b64 s[16:17], 0x20080
	s_add_u32 m0, s100, 0xe000
	v_lshl_add_u64 v[106:107], v[176:177], 0, s[16:17]
	global_load_lds_dwordx4 v[106:107], off
	s_mov_b64 s[16:17], 0x30080
	s_add_u32 m0, s100, 0xf000
	v_lshl_add_u64 v[106:107], v[176:177], 0, s[16:17]
	global_load_lds_dwordx4 v[106:107], off
	v_lshl_add_u64 v[176:177], v[176:177], 0, s[18:19]
	ds_read_b128 v[236:239], v172
	ds_read_b128 v[240:243], v172 offset:4096
	ds_read_b128 v[224:227], v164 offset:24576
	s_waitcnt lgkmcnt(4)
	v_mfma_f32_32x32x16_bf16 v[48:63], v[228:231], v[244:247], v[48:63]
	v_mfma_f32_32x32x16_bf16 v[32:47], v[228:231], v[248:251], v[32:47]
	ds_read_b128 v[228:231], v164 offset:28672
	s_waitcnt lgkmcnt(4)
	v_mfma_f32_32x32x16_bf16 v[16:31], v[232:235], v[244:247], v[16:31]
	v_mfma_f32_32x32x16_bf16 v[0:15], v[232:235], v[248:251], v[0:15]
	ds_read_b128 v[232:235], v164 offset:32768
	s_waitcnt lgkmcnt(2)
	v_mfma_f32_32x32x16_bf16 v[80:95], v[224:227], v[236:239], v[80:95]
	v_mfma_f32_32x32x16_bf16 v[64:79], v[224:227], v[240:243], v[64:79]
	ds_read_b128 v[244:247], v173
	ds_read_b128 v[248:251], v173 offset:4096
	ds_read_b128 v[224:227], v165 offset:24576
	s_waitcnt lgkmcnt(4)
	v_mfma_f32_32x32x16_bf16 v[48:63], v[228:231], v[236:239], v[48:63]
	v_mfma_f32_32x32x16_bf16 v[32:47], v[228:231], v[240:243], v[32:47]
	ds_read_b128 v[228:231], v165 offset:28672
	s_waitcnt lgkmcnt(4)
	v_mfma_f32_32x32x16_bf16 v[16:31], v[232:235], v[236:239], v[16:31]
	v_mfma_f32_32x32x16_bf16 v[0:15], v[232:235], v[240:243], v[0:15]
	ds_read_b128 v[232:235], v165 offset:32768
	s_waitcnt lgkmcnt(2)
	v_mfma_f32_32x32x16_bf16 v[80:95], v[224:227], v[244:247], v[80:95]
	v_mfma_f32_32x32x16_bf16 v[64:79], v[224:227], v[248:251], v[64:79]
	s_waitcnt lgkmcnt(0)
	s_waitcnt vmcnt(0)
	s_barrier
	s_add_u32 m0, s100, 0x6000
	v_lshl_add_u64 v[106:107], v[174:175], 0, s[96:97]
	global_load_lds_dwordx4 v[106:107], off
	s_add_u32 m0, s100, 0x7000
	v_lshl_add_u64 v[106:107], v[174:175], 0, s[50:51]
	global_load_lds_dwordx4 v[106:107], off
	ds_read_b128 v[236:239], v166 offset:49152
	ds_read_b128 v[240:243], v166 offset:53248
	ds_read_b128 v[224:227], v162
	v_mfma_f32_32x32x16_bf16 v[48:63], v[228:231], v[244:247], v[48:63]
	v_mfma_f32_32x32x16_bf16 v[32:47], v[228:231], v[248:251], v[32:47]
	ds_read_b128 v[228:231], v162 offset:4096
	v_mfma_f32_32x32x16_bf16 v[16:31], v[232:235], v[244:247], v[16:31]
	v_mfma_f32_32x32x16_bf16 v[0:15], v[232:235], v[248:251], v[0:15]
	s_add_u32 s15, s15, 2
	s_branch .Lga_loop

; template <int EPI, int MI>
; DI void gemm_tile(const GemmDesc& g, int tm, int tn, char* smem) {
;     ...
;   const int rowA = wm * (32 * MI) + r, rowB = wn * 64 + r;
;   const int hk = hh ^ ((r & 7) ^ ((r >> 3) & 3));
;     ...
;   G_GLDS(0, 0);
;   asm volatile("s_waitcnt vmcnt(0)" ::: "memory");
;   __syncthreads();
;   for (int kt = 0; kt < nk; kt += 2) {
;     if (kt + 1 < nk) G_GLDS(kt + 1, 1);
;     G_COMPUTE(0);
;     asm volatile("s_waitcnt vmcnt(0)" ::: "memory");
;     __syncthreads();
;     if (kt + 1 < nk) {
;       if (kt + 2 < nk) G_GLDS(kt + 2, 0);
;       G_COMPUTE(1);
;       asm volatile("s_waitcnt vmcnt(0)" ::: "memory");
;       __syncthreads();
;     }
;   }
.Lgd_loop:
	ds_read_b128 v[232:235], v162 offset:8192
	s_waitcnt lgkmcnt(2)
	v_mfma_f32_32x32x16_bf16 v[80:95], v[224:227], v[236:239], v[80:95]
	v_mfma_f32_32x32x16_bf16 v[64:79], v[224:227], v[240:243], v[64:79]
	s_mov_b64 s[16:17], 0x58ca080
	s_add_u32 m0, s100, 0x8000
	v_lshl_add_u64 v[106:107], v[252:253], 0, s[16:17]
	global_load_lds_dwordx4 v[106:107], off
	s_mov_b64 s[16:17], 0x58f6080
	s_add_u32 m0, s100, 0x9000
	v_lshl_add_u64 v[106:107], v[252:253], 0, s[16:17]
	global_load_lds_dwordx4 v[106:107], off
	ds_read_b128 v[244:247], v167 offset:49152
	ds_read_b128 v[248:251], v167 offset:53248
	ds_read_b128 v[224:227], v163
	s_waitcnt lgkmcnt(4)
	v_mfma_f32_32x32x16_bf16 v[48:63], v[228:231], v[236:239], v[48:63]
	v_mfma_f32_32x32x16_bf16 v[32:47], v[228:231], v[240:243], v[32:47]
	s_mov_b64 s[16:17], 0x5922080
	s_add_u32 m0, s100, 0xa000
	v_lshl_add_u64 v[106:107], v[252:253], 0, s[16:17]
	global_load_lds_dwordx4 v[106:107], off
	s_mov_b64 s[16:17], 0x594e080
	s_add_u32 m0, s100, 0xb000
	v_lshl_add_u64 v[106:107], v[252:253], 0, s[16:17]
	global_load_lds_dwordx4 v[106:107], off
	v_lshl_add_u64 v[252:253], v[252:253], 0, s[4:5]
	ds_read_b128 v[228:231], v163 offset:4096
	s_waitcnt lgkmcnt(4)
	v_mfma_f32_32x32x16_bf16 v[16:31], v[232:235], v[236:239], v[16:31]
	v_mfma_f32_32x32x16_bf16 v[0:15], v[232:235], v[240:243], v[0:15]
	s_mov_b64 s[16:17], 0x1600080
	s_add_u32 m0, s100, 0x10000
	v_lshl_add_u64 v[106:107], v[254:255], 0, s[16:17]
	global_load_lds_dwordx4 v[106:107], off
	s_mov_b64 s[16:17], 0x162c080
	s_add_u32 m0, s100, 0x11000
	v_lshl_add_u64 v[106:107], v[254:255], 0, s[16:17]
	global_load_lds_dwordx4 v[106:107], off
	ds_read_b128 v[232:235], v163 offset:8192
	s_waitcnt lgkmcnt(2)
	v_mfma_f32_32x32x16_bf16 v[80:95], v[224:227], v[244:247], v[80:95]
	v_mfma_f32_32x32x16_bf16 v[64:79], v[224:227], v[248:251], v[64:79]
	s_mov_b64 s[16:17], 0x1658080
	s_add_u32 m0, s100, 0x12000
	v_lshl_add_u64 v[106:107], v[254:255], 0, s[16:17]
	global_load_lds_dwordx4 v[106:107], off
	s_mov_b64 s[16:17], 0x1684080
	s_add_u32 m0, s100, 0x13000
	v_lshl_add_u64 v[106:107], v[254:255], 0, s[16:17]
	global_load_lds_dwordx4 v[106:107], off
	v_lshl_add_u64 v[254:255], v[254:255], 0, s[4:5]
	ds_read_b128 v[236:239], v168 offset:49152
	ds_read_b128 v[240:243], v168 offset:53248
	ds_read_b128 v[224:227], v164
	s_waitcnt lgkmcnt(4)
	v_mfma_f32_32x32x16_bf16 v[48:63], v[228:231], v[244:247], v[48:63]
	v_mfma_f32_32x32x16_bf16 v[32:47], v[228:231], v[248:251], v[32:47]
	ds_read_b128 v[228:231], v164 offset:4096
	s_waitcnt lgkmcnt(4)
	v_mfma_f32_32x32x16_bf16 v[16:31], v[232:235], v[244:247], v[16:31]
	v_mfma_f32_32x32x16_bf16 v[0:15], v[232:235], v[248:251], v[0:15]
	ds_read_b128 v[232:235], v164 offset:8192
	s_waitcnt lgkmcnt(2)
	v_mfma_f32_32x32x16_bf16 v[80:95], v[224:227], v[236:239], v[80:95]
	v_mfma_f32_32x32x16_bf16 v[64:79], v[224:227], v[240:243], v[64:79]
	ds_read_b128 v[244:247], v169 offset:49152
	ds_read_b128 v[248:251], v169 offset:53248
	ds_read_b128 v[224:227], v165
	s_waitcnt lgkmcnt(4)
	v_mfma_f32_32x32x16_bf16 v[48:63], v[228:231], v[236:239], v[48:63]
	v_mfma_f32_32x32x16_bf16 v[32:47], v[228:231], v[240:243], v[32:47]
	ds_read_b128 v[228:231], v165 offset:4096
	s_waitcnt lgkmcnt(4)
	v_mfma_f32_32x32x16_bf16 v[16:31], v[232:235], v[236:239], v[16:31]
	v_mfma_f32_32x32x16_bf16 v[0:15], v[232:235], v[240:243], v[0:15]
	ds_read_b128 v[232:235], v165 offset:8192
	s_waitcnt lgkmcnt(2)
	v_mfma_f32_32x32x16_bf16 v[80:95], v[224:227], v[244:247], v[80:95]
	v_mfma_f32_32x32x16_bf16 v[64:79], v[224:227], v[248:251], v[64:79]
	s_waitcnt lgkmcnt(0)
	s_waitcnt vmcnt(0)
	s_barrier
	s_cmp_eq_u32 s15, 42
	s_cbranch_scc1 .Lgd_noearly
	s_mov_b64 s[16:17], 0x5872080
	s_mov_b32 m0, s100
	v_lshl_add_u64 v[106:107], v[252:253], 0, s[16:17]
	global_load_lds_dwordx4 v[106:107], off
	s_mov_b64 s[16:17], 0x589e080
	s_add_u32 m0, s100, 0x1000
	v_lshl_add_u64 v[106:107], v[252:253], 0, s[16:17]
	global_load_lds_dwordx4 v[106:107], off
; template <int EPI, int MI>
; DI void gemm_tile(const GemmDesc& g, int tm, int tn, char* smem) {
;     ...
;   const int rowA = wm * (32 * MI) + r, rowB = wn * 64 + r;
;   const int hk = hh ^ ((r & 7) ^ ((r >> 3) & 3));
;     ...
;   G_GLDS(0, 0);
;   asm volatile("s_waitcnt vmcnt(0)" ::: "memory");
;   __syncthreads();
;   for (int kt = 0; kt < nk; kt += 2) {
;     if (kt + 1 < nk) G_GLDS(kt + 1, 1);
;     G_COMPUTE(0);
;     asm volatile("s_waitcnt vmcnt(0)" ::: "memory");
;     __syncthreads();
;     if (kt + 1 < nk) {
;       if (kt + 2 < nk) G_GLDS(kt + 2, 0);
;       G_COMPUTE(1);
;       asm volatile("s_waitcnt vmcnt(0)" ::: "memory");
;       __syncthreads();
;     }
;   }
.Lgd_noearly:
	ds_read_b128 v[236:239], v170
	ds_read_b128 v[240:243], v170 offset:4096
	ds_read_b128 v[224:227], v162 offset:24576
	v_mfma_f32_32x32x16_bf16 v[48:63], v[228:231], v[244:247], v[48:63]
	v_mfma_f32_32x32x16_bf16 v[32:47], v[228:231], v[248:251], v[32:47]
	ds_read_b128 v[228:231], v162 offset:28672
	v_mfma_f32_32x32x16_bf16 v[16:31], v[232:235], v[244:247], v[16:31]
	v_mfma_f32_32x32x16_bf16 v[0:15], v[232:235], v[248:251], v[0:15]
	s_cmp_eq_u32 s15, 42
	s_cbranch_scc1 .Lgd_last
	ds_read_b128 v[232:235], v162 offset:32768
	s_waitcnt lgkmcnt(2)
	v_mfma_f32_32x32x16_bf16 v[80:95], v[224:227], v[236:239], v[80:95]
	v_mfma_f32_32x32x16_bf16 v[64:79], v[224:227], v[240:243], v[64:79]
	s_mov_b64 s[16:17], 0x58ca080
	s_add_u32 m0, s100, 0x2000
	v_lshl_add_u64 v[106:107], v[252:253], 0, s[16:17]
	global_load_lds_dwordx4 v[106:107], off
	s_mov_b64 s[16:17], 0x58f6080
	s_add_u32 m0, s100, 0x3000
	v_lshl_add_u64 v[106:107], v[252:253], 0, s[16:17]
	global_load_lds_dwordx4 v[106:107], off
	ds_read_b128 v[244:247], v171
	ds_read_b128 v[248:251], v171 offset:4096
	ds_read_b128 v[224:227], v163 offset:24576
	s_waitcnt lgkmcnt(4)
	v_mfma_f32_32x32x16_bf16 v[48:63], v[228:231], v[236:239], v[48:63]
	v_mfma_f32_32x32x16_bf16 v[32:47], v[228:231], v[240:243], v[32:47]
	s_mov_b64 s[16:17], 0x5922080
	s_add_u32 m0, s100, 0x4000
	v_lshl_add_u64 v[106:107], v[252:253], 0, s[16:17]
	global_load_lds_dwordx4 v[106:107], off
	s_mov_b64 s[16:17], 0x594e080
	s_add_u32 m0, s100, 0x5000
	v_lshl_add_u64 v[106:107], v[252:253], 0, s[16:17]
	global_load_lds_dwordx4 v[106:107], off
	v_lshl_add_u64 v[252:253], v[252:253], 0, s[4:5]
	ds_read_b128 v[228:231], v163 offset:28672
	s_waitcnt lgkmcnt(4)
	v_mfma_f32_32x32x16_bf16 v[16:31], v[232:235], v[236:239], v[16:31]
	v_mfma_f32_32x32x16_bf16 v[0:15], v[232:235], v[240:243], v[0:15]
	s_mov_b64 s[16:17], 0x1600080
	s_add_u32 m0, s100, 0xc000
	v_lshl_add_u64 v[106:107], v[254:255], 0, s[16:17]
	global_load_lds_dwordx4 v[106:107], off
	s_mov_b64 s[16:17], 0x162c080
	s_add_u32 m0, s100, 0xd000
	v_lshl_add_u64 v[106:107], v[254:255], 0, s[16:17]
	global_load_lds_dwordx4 v[106:107], off
	ds_read_b128 v[232:235], v163 offset:32768
	s_waitcnt lgkmcnt(2)
	v_mfma_f32_32x32x16_bf16 v[80:95], v[224:227], v[244:247], v[80:95]
	v_mfma_f32_32x32x16_bf16 v[64:79], v[224:227], v[248:251], v[64:79]
	s_mov_b64 s[16:17], 0x1658080
	s_add_u32 m0, s100, 0xe000
	v_lshl_add_u64 v[106:107], v[254:255], 0, s[16:17]
	global_load_lds_dwordx4 v[106:107], off
	s_mov_b64 s[16:17], 0x1684080
	s_add_u32 m0, s100, 0xf000
	v_lshl_add_u64 v[106:107], v[254:255], 0, s[16:17]
	global_load_lds_dwordx4 v[106:107], off
	v_lshl_add_u64 v[254:255], v[254:255], 0, s[4:5]
	ds_read_b128 v[236:239], v172
	ds_read_b128 v[240:243], v172 offset:4096
	ds_read_b128 v[224:227], v164 offset:24576
	s_waitcnt lgkmcnt(4)
	v_mfma_f32_32x32x16_bf16 v[48:63], v[228:231], v[244:247], v[48:63]
	v_mfma_f32_32x32x16_bf16 v[32:47], v[228:231], v[248:251], v[32:47]
	ds_read_b128 v[228:231], v164 offset:28672
	s_waitcnt lgkmcnt(4)
	v_mfma_f32_32x32x16_bf16 v[16:31], v[232:235], v[244:247], v[16:31]
	v_mfma_f32_32x32x16_bf16 v[0:15], v[232:235], v[248:251], v[0:15]
	ds_read_b128 v[232:235], v164 offset:32768
	s_waitcnt lgkmcnt(2)
	v_mfma_f32_32x32x16_bf16 v[80:95], v[224:227], v[236:239], v[80:95]
	v_mfma_f32_32x32x16_bf16 v[64:79], v[224:227], v[240:243], v[64:79]
	ds_read_b128 v[244:247], v173
	ds_read_b128 v[248:251], v173 offset:4096
	ds_read_b128 v[224:227], v165 offset:24576
	s_waitcnt lgkmcnt(4)
	v_mfma_f32_32x32x16_bf16 v[48:63], v[228:231], v[236:239], v[48:63]
	v_mfma_f32_32x32x16_bf16 v[32:47], v[228:231], v[240:243], v[32:47]
	ds_read_b128 v[228:231], v165 offset:28672
	s_waitcnt lgkmcnt(4)
	v_mfma_f32_32x32x16_bf16 v[16:31], v[232:235], v[236:239], v[16:31]
	v_mfma_f32_32x32x16_bf16 v[0:15], v[232:235], v[240:243], v[0:15]
	ds_read_b128 v[232:235], v165 offset:32768
	s_waitcnt lgkmcnt(2)
	v_mfma_f32_32x32x16_bf16 v[80:95], v[224:227], v[244:247], v[80:95]
	v_mfma_f32_32x32x16_bf16 v[64:79], v[224:227], v[248:251], v[64:79]
	s_waitcnt lgkmcnt(0)
	s_waitcnt vmcnt(0)
	s_barrier
	s_mov_b64 s[16:17], 0x5872080
	s_add_u32 m0, s100, 0x6000
	v_lshl_add_u64 v[106:107], v[252:253], 0, s[16:17]
	global_load_lds_dwordx4 v[106:107], off
	s_mov_b64 s[16:17], 0x589e080
	s_add_u32 m0, s100, 0x7000
	v_lshl_add_u64 v[106:107], v[252:253], 0, s[16:17]
	global_load_lds_dwordx4 v[106:107], off
	ds_read_b128 v[236:239], v166 offset:49152
	ds_read_b128 v[240:243], v166 offset:53248
	ds_read_b128 v[224:227], v162
	v_mfma_f32_32x32x16_bf16 v[48:63], v[228:231], v[244:247], v[48:63]
	v_mfma_f32_32x32x16_bf16 v[32:47], v[228:231], v[248:251], v[32:47]
	ds_read_b128 v[228:231], v162 offset:4096
	v_mfma_f32_32x32x16_bf16 v[16:31], v[232:235], v[244:247], v[16:31]
	v_mfma_f32_32x32x16_bf16 v[0:15], v[232:235], v[248:251], v[0:15]
	s_add_u32 s15, s15, 2
	s_branch .Lgd_loop

; template <int EPI, int MI>
; DI void gemm_tile(const GemmDesc& g, int tm, int tn, char* smem) {
;     ...
;   const int rowA = wm * (32 * MI) + r, rowB = wn * 64 + r;
;   const int hk = hh ^ ((r & 7) ^ ((r >> 3) & 3));
;     ...
;   G_GLDS(0, 0);
;   asm volatile("s_waitcnt vmcnt(0)" ::: "memory");
;   __syncthreads();
;   for (int kt = 0; kt < nk; kt += 2) {
;     if (kt + 1 < nk) G_GLDS(kt + 1, 1);
;     G_COMPUTE(0);
;     asm volatile("s_waitcnt vmcnt(0)" ::: "memory");
;     __syncthreads();
;     if (kt + 1 < nk) {
;       if (kt + 2 < nk) G_GLDS(kt + 2, 0);
;       G_COMPUTE(1);
;       asm volatile("s_waitcnt vmcnt(0)" ::: "memory");
;       __syncthreads();
;     }
;   }
.Lgw_loop:
	ds_read_b128 v[232:235], v162 offset:8192
	s_waitcnt lgkmcnt(2)
	v_mfma_f32_32x32x16_bf16 v[80:95], v[224:227], v[236:239], v[80:95]
	v_mfma_f32_32x32x16_bf16 v[64:79], v[224:227], v[240:243], v[64:79]
	s_add_u32 m0, s100, 0x8000
	v_lshl_add_u64 v[106:107], v[252:253], 0, s[24:25]
	global_load_lds_dwordx4 v[106:107], off
	s_add_u32 m0, s100, 0x9000
	v_lshl_add_u64 v[106:107], v[252:253], 0, s[26:27]
	global_load_lds_dwordx4 v[106:107], off
	ds_read_b128 v[244:247], v167 offset:49152
	ds_read_b128 v[248:251], v167 offset:53248
	ds_read_b128 v[224:227], v163
	s_waitcnt lgkmcnt(4)
	v_mfma_f32_32x32x16_bf16 v[48:63], v[228:231], v[236:239], v[48:63]
	v_mfma_f32_32x32x16_bf16 v[32:47], v[228:231], v[240:243], v[32:47]
	s_add_u32 m0, s100, 0xa000
	v_lshl_add_u64 v[106:107], v[252:253], 0, s[28:29]
	global_load_lds_dwordx4 v[106:107], off
	s_add_u32 m0, s100, 0xb000
	v_lshl_add_u64 v[106:107], v[252:253], 0, s[30:31]
	global_load_lds_dwordx4 v[106:107], off
	v_lshl_add_u64 v[252:253], v[252:253], 0, s[0:1]
	ds_read_b128 v[228:231], v163 offset:4096
	s_waitcnt lgkmcnt(4)
	v_mfma_f32_32x32x16_bf16 v[16:31], v[232:235], v[236:239], v[16:31]
	v_mfma_f32_32x32x16_bf16 v[0:15], v[232:235], v[240:243], v[0:15]
	s_mov_b64 s[16:17], 0x2100080
	s_add_u32 m0, s100, 0x10000
	v_lshl_add_u64 v[106:107], v[254:255], 0, s[16:17]
	global_load_lds_dwordx4 v[106:107], off
	s_mov_b64 s[16:17], 0x2110080
	s_add_u32 m0, s100, 0x11000
	v_lshl_add_u64 v[106:107], v[254:255], 0, s[16:17]
	global_load_lds_dwordx4 v[106:107], off
	ds_read_b128 v[232:235], v163 offset:8192
	s_waitcnt lgkmcnt(2)
	v_mfma_f32_32x32x16_bf16 v[80:95], v[224:227], v[244:247], v[80:95]
	v_mfma_f32_32x32x16_bf16 v[64:79], v[224:227], v[248:251], v[64:79]
	s_mov_b64 s[16:17], 0x2120080
	s_add_u32 m0, s100, 0x12000
	v_lshl_add_u64 v[106:107], v[254:255], 0, s[16:17]
	global_load_lds_dwordx4 v[106:107], off
	s_mov_b64 s[16:17], 0x2130080
	s_add_u32 m0, s100, 0x13000
	v_lshl_add_u64 v[106:107], v[254:255], 0, s[16:17]
	global_load_lds_dwordx4 v[106:107], off
	v_lshl_add_u64 v[254:255], v[254:255], 0, s[0:1]
	ds_read_b128 v[236:239], v168 offset:49152
	ds_read_b128 v[240:243], v168 offset:53248
	ds_read_b128 v[224:227], v164
	s_waitcnt lgkmcnt(4)
	v_mfma_f32_32x32x16_bf16 v[48:63], v[228:231], v[244:247], v[48:63]
	v_mfma_f32_32x32x16_bf16 v[32:47], v[228:231], v[248:251], v[32:47]
	ds_read_b128 v[228:231], v164 offset:4096
	s_waitcnt lgkmcnt(4)
	v_mfma_f32_32x32x16_bf16 v[16:31], v[232:235], v[244:247], v[16:31]
	v_mfma_f32_32x32x16_bf16 v[0:15], v[232:235], v[248:251], v[0:15]
	ds_read_b128 v[232:235], v164 offset:8192
	s_waitcnt lgkmcnt(2)
	v_mfma_f32_32x32x16_bf16 v[80:95], v[224:227], v[236:239], v[80:95]
	v_mfma_f32_32x32x16_bf16 v[64:79], v[224:227], v[240:243], v[64:79]
	ds_read_b128 v[244:247], v169 offset:49152
	ds_read_b128 v[248:251], v169 offset:53248
	ds_read_b128 v[224:227], v165
	s_waitcnt lgkmcnt(4)
	v_mfma_f32_32x32x16_bf16 v[48:63], v[228:231], v[236:239], v[48:63]
	v_mfma_f32_32x32x16_bf16 v[32:47], v[228:231], v[240:243], v[32:47]
	ds_read_b128 v[228:231], v165 offset:4096
	s_waitcnt lgkmcnt(4)
	v_mfma_f32_32x32x16_bf16 v[16:31], v[232:235], v[236:239], v[16:31]
	v_mfma_f32_32x32x16_bf16 v[0:15], v[232:235], v[240:243], v[0:15]
	ds_read_b128 v[232:235], v165 offset:8192
	s_waitcnt lgkmcnt(2)
	v_mfma_f32_32x32x16_bf16 v[80:95], v[224:227], v[244:247], v[80:95]
	v_mfma_f32_32x32x16_bf16 v[64:79], v[224:227], v[248:251], v[64:79]
	s_waitcnt lgkmcnt(0)
	s_waitcnt vmcnt(0)
	s_barrier
	s_cmp_eq_u32 s101, 14
	s_cbranch_scc1 .Lgw_noearly
	s_mov_b32 m0, s100
	v_lshl_add_u64 v[106:107], v[252:253], 0, s[96:97]
	global_load_lds_dwordx4 v[106:107], off
	s_add_u32 m0, s100, 0x1000
	v_lshl_add_u64 v[106:107], v[252:253], 0, s[50:51]
	global_load_lds_dwordx4 v[106:107], off
; template <int EPI, int MI>
; DI void gemm_tile(const GemmDesc& g, int tm, int tn, char* smem) {
;     ...
;   const int rowA = wm * (32 * MI) + r, rowB = wn * 64 + r;
;   const int hk = hh ^ ((r & 7) ^ ((r >> 3) & 3));
;     ...
;   G_GLDS(0, 0);
;   asm volatile("s_waitcnt vmcnt(0)" ::: "memory");
;   __syncthreads();
;   for (int kt = 0; kt < nk; kt += 2) {
;     if (kt + 1 < nk) G_GLDS(kt + 1, 1);
;     G_COMPUTE(0);
;     asm volatile("s_waitcnt vmcnt(0)" ::: "memory");
;     __syncthreads();
;     if (kt + 1 < nk) {
;       if (kt + 2 < nk) G_GLDS(kt + 2, 0);
;       G_COMPUTE(1);
;       asm volatile("s_waitcnt vmcnt(0)" ::: "memory");
;       __syncthreads();
;     }
;   }
.Lgw_noearly:
	ds_read_b128 v[236:239], v170
	ds_read_b128 v[240:243], v170 offset:4096
	ds_read_b128 v[224:227], v162 offset:24576
	v_mfma_f32_32x32x16_bf16 v[48:63], v[228:231], v[244:247], v[48:63]
	v_mfma_f32_32x32x16_bf16 v[32:47], v[228:231], v[248:251], v[32:47]
	ds_read_b128 v[228:231], v162 offset:28672
	v_mfma_f32_32x32x16_bf16 v[16:31], v[232:235], v[244:247], v[16:31]
	v_mfma_f32_32x32x16_bf16 v[0:15], v[232:235], v[248:251], v[0:15]
	s_cmp_eq_u32 s101, 14
	s_cbranch_scc1 .Lgw_last
	ds_read_b128 v[232:235], v162 offset:32768
	s_waitcnt lgkmcnt(2)
	v_mfma_f32_32x32x16_bf16 v[80:95], v[224:227], v[236:239], v[80:95]
	v_mfma_f32_32x32x16_bf16 v[64:79], v[224:227], v[240:243], v[64:79]
	s_add_u32 m0, s100, 0x2000
	v_lshl_add_u64 v[106:107], v[252:253], 0, s[24:25]
	global_load_lds_dwordx4 v[106:107], off
	s_add_u32 m0, s100, 0x3000
	v_lshl_add_u64 v[106:107], v[252:253], 0, s[26:27]
	global_load_lds_dwordx4 v[106:107], off
	ds_read_b128 v[244:247], v171
	ds_read_b128 v[248:251], v171 offset:4096
	ds_read_b128 v[224:227], v163 offset:24576
	s_waitcnt lgkmcnt(4)
	v_mfma_f32_32x32x16_bf16 v[48:63], v[228:231], v[236:239], v[48:63]
	v_mfma_f32_32x32x16_bf16 v[32:47], v[228:231], v[240:243], v[32:47]
	s_add_u32 m0, s100, 0x4000
	v_lshl_add_u64 v[106:107], v[252:253], 0, s[28:29]
	global_load_lds_dwordx4 v[106:107], off
	s_add_u32 m0, s100, 0x5000
	v_lshl_add_u64 v[106:107], v[252:253], 0, s[30:31]
	global_load_lds_dwordx4 v[106:107], off
	v_lshl_add_u64 v[252:253], v[252:253], 0, s[0:1]
	ds_read_b128 v[228:231], v163 offset:28672
	s_waitcnt lgkmcnt(4)
	v_mfma_f32_32x32x16_bf16 v[16:31], v[232:235], v[236:239], v[16:31]
	v_mfma_f32_32x32x16_bf16 v[0:15], v[232:235], v[240:243], v[0:15]
	s_mov_b64 s[16:17], 0x2100080
	s_add_u32 m0, s100, 0xc000
	v_lshl_add_u64 v[106:107], v[254:255], 0, s[16:17]
	global_load_lds_dwordx4 v[106:107], off
	s_mov_b64 s[16:17], 0x2110080
	s_add_u32 m0, s100, 0xd000
	v_lshl_add_u64 v[106:107], v[254:255], 0, s[16:17]
	global_load_lds_dwordx4 v[106:107], off
	ds_read_b128 v[232:235], v163 offset:32768
	s_waitcnt lgkmcnt(2)
	v_mfma_f32_32x32x16_bf16 v[80:95], v[224:227], v[244:247], v[80:95]
	v_mfma_f32_32x32x16_bf16 v[64:79], v[224:227], v[248:251], v[64:79]
	s_mov_b64 s[16:17], 0x2120080
	s_add_u32 m0, s100, 0xe000
	v_lshl_add_u64 v[106:107], v[254:255], 0, s[16:17]
	global_load_lds_dwordx4 v[106:107], off
	s_mov_b64 s[16:17], 0x2130080
	s_add_u32 m0, s100, 0xf000
	v_lshl_add_u64 v[106:107], v[254:255], 0, s[16:17]
	global_load_lds_dwordx4 v[106:107], off
	v_lshl_add_u64 v[254:255], v[254:255], 0, s[0:1]
	ds_read_b128 v[236:239], v172
	ds_read_b128 v[240:243], v172 offset:4096
	ds_read_b128 v[224:227], v164 offset:24576
	s_waitcnt lgkmcnt(4)
	v_mfma_f32_32x32x16_bf16 v[48:63], v[228:231], v[244:247], v[48:63]
	v_mfma_f32_32x32x16_bf16 v[32:47], v[228:231], v[248:251], v[32:47]
	ds_read_b128 v[228:231], v164 offset:28672
	s_waitcnt lgkmcnt(4)
	v_mfma_f32_32x32x16_bf16 v[16:31], v[232:235], v[244:247], v[16:31]
	v_mfma_f32_32x32x16_bf16 v[0:15], v[232:235], v[248:251], v[0:15]
	ds_read_b128 v[232:235], v164 offset:32768
	s_waitcnt lgkmcnt(2)
	v_mfma_f32_32x32x16_bf16 v[80:95], v[224:227], v[236:239], v[80:95]
	v_mfma_f32_32x32x16_bf16 v[64:79], v[224:227], v[240:243], v[64:79]
	ds_read_b128 v[244:247], v173
	ds_read_b128 v[248:251], v173 offset:4096
	ds_read_b128 v[224:227], v165 offset:24576
	s_waitcnt lgkmcnt(4)
	v_mfma_f32_32x32x16_bf16 v[48:63], v[228:231], v[236:239], v[48:63]
	v_mfma_f32_32x32x16_bf16 v[32:47], v[228:231], v[240:243], v[32:47]
	ds_read_b128 v[228:231], v165 offset:28672
	s_waitcnt lgkmcnt(4)
	v_mfma_f32_32x32x16_bf16 v[16:31], v[232:235], v[236:239], v[16:31]
	v_mfma_f32_32x32x16_bf16 v[0:15], v[232:235], v[240:243], v[0:15]
	ds_read_b128 v[232:235], v165 offset:32768
	s_waitcnt lgkmcnt(2)
	v_mfma_f32_32x32x16_bf16 v[80:95], v[224:227], v[244:247], v[80:95]
	v_mfma_f32_32x32x16_bf16 v[64:79], v[224:227], v[248:251], v[64:79]
	s_waitcnt lgkmcnt(0)
	s_waitcnt vmcnt(0)
	s_barrier
	s_add_u32 m0, s100, 0x6000
	v_lshl_add_u64 v[106:107], v[252:253], 0, s[96:97]
	global_load_lds_dwordx4 v[106:107], off
	s_add_u32 m0, s100, 0x7000
	v_lshl_add_u64 v[106:107], v[252:253], 0, s[50:51]
	global_load_lds_dwordx4 v[106:107], off
	ds_read_b128 v[236:239], v166 offset:49152
	ds_read_b128 v[240:243], v166 offset:53248
	ds_read_b128 v[224:227], v162
	v_mfma_f32_32x32x16_bf16 v[48:63], v[228:231], v[244:247], v[48:63]
	v_mfma_f32_32x32x16_bf16 v[32:47], v[228:231], v[248:251], v[32:47]
	ds_read_b128 v[228:231], v162 offset:4096
	v_mfma_f32_32x32x16_bf16 v[16:31], v[232:235], v[244:247], v[16:31]
	v_mfma_f32_32x32x16_bf16 v[0:15], v[232:235], v[248:251], v[0:15]
	s_add_u32 s101, s101, 2
	s_branch .Lgw_loop

; template <int EPI, int MI>
; DI void gemm_tile(const GemmDesc& g, int tm, int tn, char* smem) {
;     ...
;   const int rowA = wm * (32 * MI) + r, rowB = wn * 64 + r;
;   const int hk = hh ^ ((r & 7) ^ ((r >> 3) & 3));
;     ...
;   G_GLDS(0, 0);
;   asm volatile("s_waitcnt vmcnt(0)" ::: "memory");
;   __syncthreads();
;   for (int kt = 0; kt < nk; kt += 2) {
;     if (kt + 1 < nk) G_GLDS(kt + 1, 1);
;     G_COMPUTE(0);
;     asm volatile("s_waitcnt vmcnt(0)" ::: "memory");
;     __syncthreads();
;     if (kt + 1 < nk) {
;       if (kt + 2 < nk) G_GLDS(kt + 2, 0);
;       G_COMPUTE(1);
;       asm volatile("s_waitcnt vmcnt(0)" ::: "memory");
;       __syncthreads();
;     }
;   }
.Lgc_loop:
	ds_read_b128 v[248:251], v103 offset:32768
	ds_read_b128 v[252:255], v103 offset:36864
	ds_read_b128 v[232:235], v99
	s_waitcnt lgkmcnt(4)
	v_mfma_f32_32x32x16_bf16 v[48:63], v[224:227], v[240:243], v[48:63]
	v_mfma_f32_32x32x16_bf16 v[32:47], v[224:227], v[244:247], v[32:47]
	s_add_u32 m0, s100, 0x6000
	v_lshl_add_u64 v[106:107], v[72:73], 0, s[24:25]
	global_load_lds_dwordx4 v[106:107], off
	s_add_u32 m0, s100, 0x7000
	v_lshl_add_u64 v[106:107], v[72:73], 0, s[26:27]
	global_load_lds_dwordx4 v[106:107], off
	v_lshl_add_u64 v[72:73], v[72:73], 0, s[44:45]
	ds_read_b128 v[236:239], v99 offset:4096
	s_waitcnt lgkmcnt(4)
	v_mfma_f32_32x32x16_bf16 v[16:31], v[228:231], v[240:243], v[16:31]
	v_mfma_f32_32x32x16_bf16 v[0:15], v[228:231], v[244:247], v[0:15]
	s_mov_b64 s[0:1], 0xb00080
	s_add_u32 m0, s100, 0xc000
	v_lshl_add_u64 v[106:107], v[74:75], 0, s[0:1]
	global_load_lds_dwordx4 v[106:107], off
	s_mov_b64 s[0:1], 0xb10080
	s_add_u32 m0, s100, 0xd000
	v_lshl_add_u64 v[106:107], v[74:75], 0, s[0:1]
	global_load_lds_dwordx4 v[106:107], off
	ds_read_b128 v[240:243], v104 offset:32768
	ds_read_b128 v[244:247], v104 offset:36864
	ds_read_b128 v[224:227], v100
	s_waitcnt lgkmcnt(4)
	v_mfma_f32_32x32x16_bf16 v[48:63], v[232:235], v[248:251], v[48:63]
	v_mfma_f32_32x32x16_bf16 v[32:47], v[232:235], v[252:255], v[32:47]
	s_mov_b64 s[0:1], 0xb20080
	s_add_u32 m0, s100, 0xe000
	v_lshl_add_u64 v[106:107], v[74:75], 0, s[0:1]
	global_load_lds_dwordx4 v[106:107], off
	s_mov_b64 s[0:1], 0xb30080
	s_add_u32 m0, s100, 0xf000
	v_lshl_add_u64 v[106:107], v[74:75], 0, s[0:1]
	global_load_lds_dwordx4 v[106:107], off
	v_lshl_add_u64 v[74:75], v[74:75], 0, s[44:45]
	ds_read_b128 v[228:231], v100 offset:4096
	s_waitcnt lgkmcnt(4)
	v_mfma_f32_32x32x16_bf16 v[16:31], v[236:239], v[248:251], v[16:31]
	v_mfma_f32_32x32x16_bf16 v[0:15], v[236:239], v[252:255], v[0:15]
	ds_read_b128 v[248:251], v105 offset:32768
	ds_read_b128 v[252:255], v105 offset:36864
	ds_read_b128 v[232:235], v101
	s_waitcnt lgkmcnt(4)
	v_mfma_f32_32x32x16_bf16 v[48:63], v[224:227], v[240:243], v[48:63]
	v_mfma_f32_32x32x16_bf16 v[32:47], v[224:227], v[244:247], v[32:47]
	ds_read_b128 v[236:239], v101 offset:4096
	s_waitcnt lgkmcnt(4)
	v_mfma_f32_32x32x16_bf16 v[16:31], v[228:231], v[240:243], v[16:31]
	v_mfma_f32_32x32x16_bf16 v[0:15], v[228:231], v[244:247], v[0:15]
	s_waitcnt lgkmcnt(0)
	s_waitcnt vmcnt(0)
	s_barrier
	s_cmp_eq_u32 s101, 14
	s_cbranch_scc1 .Lgc_noearly
	s_mov_b32 m0, s100
	v_lshl_add_u64 v[106:107], v[72:73], 0, s[96:97]
	global_load_lds_dwordx4 v[106:107], off
	s_add_u32 m0, s100, 0x1000
	v_lshl_add_u64 v[106:107], v[72:73], 0, s[50:51]
	global_load_lds_dwordx4 v[106:107], off
.Lgc_noearly:
	ds_read_b128 v[240:243], v102 offset:49152
	ds_read_b128 v[244:247], v102 offset:53248
	ds_read_b128 v[224:227], v98 offset:16384
	v_mfma_f32_32x32x16_bf16 v[48:63], v[232:235], v[248:251], v[48:63]
	v_mfma_f32_32x32x16_bf16 v[32:47], v[232:235], v[252:255], v[32:47]
	ds_read_b128 v[228:231], v98 offset:20480
	v_mfma_f32_32x32x16_bf16 v[16:31], v[236:239], v[248:251], v[16:31]
	v_mfma_f32_32x32x16_bf16 v[0:15], v[236:239], v[252:255], v[0:15]
	s_cmp_eq_u32 s101, 14
	s_cbranch_scc1 .Lgc_last
	ds_read_b128 v[248:251], v103 offset:49152
	ds_read_b128 v[252:255], v103 offset:53248
	ds_read_b128 v[232:235], v99 offset:16384
	s_waitcnt lgkmcnt(4)
	v_mfma_f32_32x32x16_bf16 v[48:63], v[224:227], v[240:243], v[48:63]
	v_mfma_f32_32x32x16_bf16 v[32:47], v[224:227], v[244:247], v[32:47]
	s_add_u32 m0, s100, 0x2000
	v_lshl_add_u64 v[106:107], v[72:73], 0, s[24:25]
	global_load_lds_dwordx4 v[106:107], off
	s_add_u32 m0, s100, 0x3000
	v_lshl_add_u64 v[106:107], v[72:73], 0, s[26:27]
	global_load_lds_dwordx4 v[106:107], off
	v_lshl_add_u64 v[72:73], v[72:73], 0, s[44:45]
	ds_read_b128 v[236:239], v99 offset:20480
	s_waitcnt lgkmcnt(4)
	v_mfma_f32_32x32x16_bf16 v[16:31], v[228:231], v[240:243], v[16:31]
	v_mfma_f32_32x32x16_bf16 v[0:15], v[228:231], v[244:247], v[0:15]
	s_mov_b64 s[0:1], 0xb00080
	s_add_u32 m0, s100, 0x8000
	v_lshl_add_u64 v[106:107], v[74:75], 0, s[0:1]
	global_load_lds_dwordx4 v[106:107], off
	s_mov_b64 s[0:1], 0xb10080
	s_add_u32 m0, s100, 0x9000
	v_lshl_add_u64 v[106:107], v[74:75], 0, s[0:1]
	global_load_lds_dwordx4 v[106:107], off
	ds_read_b128 v[240:243], v104 offset:49152
	ds_read_b128 v[244:247], v104 offset:53248
	ds_read_b128 v[224:227], v100 offset:16384
	s_waitcnt lgkmcnt(4)
	v_mfma_f32_32x32x16_bf16 v[48:63], v[232:235], v[248:251], v[48:63]
	v_mfma_f32_32x32x16_bf16 v[32:47], v[232:235], v[252:255], v[32:47]
	s_mov_b64 s[0:1], 0xb20080
	s_add_u32 m0, s100, 0xa000
	v_lshl_add_u64 v[106:107], v[74:75], 0, s[0:1]
	global_load_lds_dwordx4 v[106:107], off
	s_mov_b64 s[0:1], 0xb30080
	s_add_u32 m0, s100, 0xb000
	v_lshl_add_u64 v[106:107], v[74:75], 0, s[0:1]
	global_load_lds_dwordx4 v[106:107], off
	v_lshl_add_u64 v[74:75], v[74:75], 0, s[44:45]
	ds_read_b128 v[228:231], v100 offset:20480
	s_waitcnt lgkmcnt(4)
	v_mfma_f32_32x32x16_bf16 v[16:31], v[236:239], v[248:251], v[16:31]
	v_mfma_f32_32x32x16_bf16 v[0:15], v[236:239], v[252:255], v[0:15]
	ds_read_b128 v[248:251], v105 offset:49152
	ds_read_b128 v[252:255], v105 offset:53248
	ds_read_b128 v[232:235], v101 offset:16384
	s_waitcnt lgkmcnt(4)
	v_mfma_f32_32x32x16_bf16 v[48:63], v[224:227], v[240:243], v[48:63]
	v_mfma_f32_32x32x16_bf16 v[32:47], v[224:227], v[244:247], v[32:47]
	ds_read_b128 v[236:239], v101 offset:20480
	s_waitcnt lgkmcnt(4)
	v_mfma_f32_32x32x16_bf16 v[16:31], v[228:231], v[240:243], v[16:31]
	v_mfma_f32_32x32x16_bf16 v[0:15], v[228:231], v[244:247], v[0:15]
	s_waitcnt lgkmcnt(0)
	s_waitcnt vmcnt(0)
	s_barrier
	s_add_u32 m0, s100, 0x4000
	v_lshl_add_u64 v[106:107], v[72:73], 0, s[96:97]
	global_load_lds_dwordx4 v[106:107], off
	s_add_u32 m0, s100, 0x5000
	v_lshl_add_u64 v[106:107], v[72:73], 0, s[50:51]
	global_load_lds_dwordx4 v[106:107], off
	ds_read_b128 v[240:243], v102 offset:32768
	ds_read_b128 v[244:247], v102 offset:36864
	ds_read_b128 v[224:227], v98
	v_mfma_f32_32x32x16_bf16 v[48:63], v[232:235], v[248:251], v[48:63]
	v_mfma_f32_32x32x16_bf16 v[32:47], v[232:235], v[252:255], v[32:47]
	ds_read_b128 v[228:231], v98 offset:4096
	v_mfma_f32_32x32x16_bf16 v[16:31], v[236:239], v[248:251], v[16:31]
	v_mfma_f32_32x32x16_bf16 v[0:15], v[236:239], v[252:255], v[0:15]
	s_add_u32 s101, s101, 2
	s_branch .Lgc_loop

; template <int EPI, int MI>
; DI void gemm_tile(const GemmDesc& g, int tm, int tn, char* smem) {
;     ...
;   const int rowA = wm * (32 * MI) + r, rowB = wn * 64 + r;
;   const int hk = hh ^ ((r & 7) ^ ((r >> 3) & 3));
;     ...
;   G_GLDS(0, 0);
;   asm volatile("s_waitcnt vmcnt(0)" ::: "memory");
;   __syncthreads();
;   for (int kt = 0; kt < nk; kt += 2) {
;     if (kt + 1 < nk) G_GLDS(kt + 1, 1);
;     G_COMPUTE(0);
;     asm volatile("s_waitcnt vmcnt(0)" ::: "memory");
;     __syncthreads();
;     if (kt + 1 < nk) {
;       if (kt + 2 < nk) G_GLDS(kt + 2, 0);
;       G_COMPUTE(1);
;       asm volatile("s_waitcnt vmcnt(0)" ::: "memory");
;       __syncthreads();
;     }
;   }
.Lgb_loop:
	ds_read_b128 v[232:235], v162 offset:8192
	s_waitcnt lgkmcnt(2)
	v_mfma_f32_32x32x16_bf16 v[80:95], v[224:227], v[236:239], v[80:95]
	v_mfma_f32_32x32x16_bf16 v[64:79], v[224:227], v[240:243], v[64:79]
	s_add_u32 m0, s100, 0x8000
	v_lshl_add_u64 v[106:107], v[252:253], 0, s[24:25]
	global_load_lds_dwordx4 v[106:107], off
	s_add_u32 m0, s100, 0x9000
	v_lshl_add_u64 v[106:107], v[252:253], 0, s[26:27]
	global_load_lds_dwordx4 v[106:107], off
	ds_read_b128 v[244:247], v167 offset:49152
	ds_read_b128 v[248:251], v167 offset:53248
	ds_read_b128 v[224:227], v163
	s_waitcnt lgkmcnt(4)
	v_mfma_f32_32x32x16_bf16 v[48:63], v[228:231], v[236:239], v[48:63]
	v_mfma_f32_32x32x16_bf16 v[32:47], v[228:231], v[240:243], v[32:47]
	s_add_u32 m0, s100, 0xa000
	v_lshl_add_u64 v[106:107], v[252:253], 0, s[28:29]
	global_load_lds_dwordx4 v[106:107], off
	s_add_u32 m0, s100, 0xb000
	v_lshl_add_u64 v[106:107], v[252:253], 0, s[30:31]
	global_load_lds_dwordx4 v[106:107], off
	v_lshl_add_u64 v[252:253], v[252:253], 0, s[0:1]
	ds_read_b128 v[228:231], v163 offset:4096
	s_waitcnt lgkmcnt(4)
	v_mfma_f32_32x32x16_bf16 v[16:31], v[232:235], v[236:239], v[16:31]
	v_mfma_f32_32x32x16_bf16 v[0:15], v[232:235], v[240:243], v[0:15]
	s_mov_b64 s[16:17], 0xb00080
	s_add_u32 m0, s100, 0x10000
	v_lshl_add_u64 v[106:107], v[254:255], 0, s[16:17]
	global_load_lds_dwordx4 v[106:107], off
	s_mov_b64 s[16:17], 0xb10080
	s_add_u32 m0, s100, 0x11000
	v_lshl_add_u64 v[106:107], v[254:255], 0, s[16:17]
	global_load_lds_dwordx4 v[106:107], off
	ds_read_b128 v[232:235], v163 offset:8192
	s_waitcnt lgkmcnt(2)
	v_mfma_f32_32x32x16_bf16 v[80:95], v[224:227], v[244:247], v[80:95]
	v_mfma_f32_32x32x16_bf16 v[64:79], v[224:227], v[248:251], v[64:79]
	s_mov_b64 s[16:17], 0xb20080
	s_add_u32 m0, s100, 0x12000
	v_lshl_add_u64 v[106:107], v[254:255], 0, s[16:17]
	global_load_lds_dwordx4 v[106:107], off
	s_mov_b64 s[16:17], 0xb30080
	s_add_u32 m0, s100, 0x13000
	v_lshl_add_u64 v[106:107], v[254:255], 0, s[16:17]
	global_load_lds_dwordx4 v[106:107], off
	v_lshl_add_u64 v[254:255], v[254:255], 0, s[0:1]
	ds_read_b128 v[236:239], v168 offset:49152
	ds_read_b128 v[240:243], v168 offset:53248
	ds_read_b128 v[224:227], v164
	s_waitcnt lgkmcnt(4)
	v_mfma_f32_32x32x16_bf16 v[48:63], v[228:231], v[244:247], v[48:63]
	v_mfma_f32_32x32x16_bf16 v[32:47], v[228:231], v[248:251], v[32:47]
	ds_read_b128 v[228:231], v164 offset:4096
	s_waitcnt lgkmcnt(4)
	v_mfma_f32_32x32x16_bf16 v[16:31], v[232:235], v[244:247], v[16:31]
	v_mfma_f32_32x32x16_bf16 v[0:15], v[232:235], v[248:251], v[0:15]
	ds_read_b128 v[232:235], v164 offset:8192
	s_waitcnt lgkmcnt(2)
	v_mfma_f32_32x32x16_bf16 v[80:95], v[224:227], v[236:239], v[80:95]
	v_mfma_f32_32x32x16_bf16 v[64:79], v[224:227], v[240:243], v[64:79]
	ds_read_b128 v[244:247], v169 offset:49152
	ds_read_b128 v[248:251], v169 offset:53248
	ds_read_b128 v[224:227], v165
	s_waitcnt lgkmcnt(4)
	v_mfma_f32_32x32x16_bf16 v[48:63], v[228:231], v[236:239], v[48:63]
	v_mfma_f32_32x32x16_bf16 v[32:47], v[228:231], v[240:243], v[32:47]
	ds_read_b128 v[228:231], v165 offset:4096
	s_waitcnt lgkmcnt(4)
	v_mfma_f32_32x32x16_bf16 v[16:31], v[232:235], v[236:239], v[16:31]
	v_mfma_f32_32x32x16_bf16 v[0:15], v[232:235], v[240:243], v[0:15]
	ds_read_b128 v[232:235], v165 offset:8192
	s_waitcnt lgkmcnt(2)
	v_mfma_f32_32x32x16_bf16 v[80:95], v[224:227], v[244:247], v[80:95]
	v_mfma_f32_32x32x16_bf16 v[64:79], v[224:227], v[248:251], v[64:79]
	s_waitcnt lgkmcnt(0)
	s_waitcnt vmcnt(0)
	s_barrier
	s_cmp_eq_u32 s101, 14
	s_cbranch_scc1 .Lgb_noearly
	s_mov_b32 m0, s100
	v_lshl_add_u64 v[106:107], v[252:253], 0, s[96:97]
	global_load_lds_dwordx4 v[106:107], off
	s_add_u32 m0, s100, 0x1000
	v_lshl_add_u64 v[106:107], v[252:253], 0, s[50:51]
	global_load_lds_dwordx4 v[106:107], off
; template <int EPI, int MI>
; DI void gemm_tile(const GemmDesc& g, int tm, int tn, char* smem) {
;     ...
;   const int rowA = wm * (32 * MI) + r, rowB = wn * 64 + r;
;   const int hk = hh ^ ((r & 7) ^ ((r >> 3) & 3));
;     ...
;   G_GLDS(0, 0);
;   asm volatile("s_waitcnt vmcnt(0)" ::: "memory");
;   __syncthreads();
;   for (int kt = 0; kt < nk; kt += 2) {
;     if (kt + 1 < nk) G_GLDS(kt + 1, 1);
;     G_COMPUTE(0);
;     asm volatile("s_waitcnt vmcnt(0)" ::: "memory");
;     __syncthreads();
;     if (kt + 1 < nk) {
;       if (kt + 2 < nk) G_GLDS(kt + 2, 0);
;       G_COMPUTE(1);
;       asm volatile("s_waitcnt vmcnt(0)" ::: "memory");
;       __syncthreads();
;     }
;   }
.Lgb_noearly:
	ds_read_b128 v[236:239], v170
	ds_read_b128 v[240:243], v170 offset:4096
	ds_read_b128 v[224:227], v162 offset:24576
	v_mfma_f32_32x32x16_bf16 v[48:63], v[228:231], v[244:247], v[48:63]
	v_mfma_f32_32x32x16_bf16 v[32:47], v[228:231], v[248:251], v[32:47]
	ds_read_b128 v[228:231], v162 offset:28672
	v_mfma_f32_32x32x16_bf16 v[16:31], v[232:235], v[244:247], v[16:31]
	v_mfma_f32_32x32x16_bf16 v[0:15], v[232:235], v[248:251], v[0:15]
	s_cmp_eq_u32 s101, 14
	s_cbranch_scc1 .Lgb_last
	ds_read_b128 v[232:235], v162 offset:32768
	s_waitcnt lgkmcnt(2)
	v_mfma_f32_32x32x16_bf16 v[80:95], v[224:227], v[236:239], v[80:95]
	v_mfma_f32_32x32x16_bf16 v[64:79], v[224:227], v[240:243], v[64:79]
	s_add_u32 m0, s100, 0x2000
	v_lshl_add_u64 v[106:107], v[252:253], 0, s[24:25]
	global_load_lds_dwordx4 v[106:107], off
	s_add_u32 m0, s100, 0x3000
	v_lshl_add_u64 v[106:107], v[252:253], 0, s[26:27]
	global_load_lds_dwordx4 v[106:107], off
	ds_read_b128 v[244:247], v171
	ds_read_b128 v[248:251], v171 offset:4096
	ds_read_b128 v[224:227], v163 offset:24576
	s_waitcnt lgkmcnt(4)
	v_mfma_f32_32x32x16_bf16 v[48:63], v[228:231], v[236:239], v[48:63]
	v_mfma_f32_32x32x16_bf16 v[32:47], v[228:231], v[240:243], v[32:47]
	s_add_u32 m0, s100, 0x4000
	v_lshl_add_u64 v[106:107], v[252:253], 0, s[28:29]
	global_load_lds_dwordx4 v[106:107], off
	s_add_u32 m0, s100, 0x5000
	v_lshl_add_u64 v[106:107], v[252:253], 0, s[30:31]
	global_load_lds_dwordx4 v[106:107], off
	v_lshl_add_u64 v[252:253], v[252:253], 0, s[0:1]
	ds_read_b128 v[228:231], v163 offset:28672
	s_waitcnt lgkmcnt(4)
	v_mfma_f32_32x32x16_bf16 v[16:31], v[232:235], v[236:239], v[16:31]
	v_mfma_f32_32x32x16_bf16 v[0:15], v[232:235], v[240:243], v[0:15]
	s_mov_b64 s[16:17], 0xb00080
	s_add_u32 m0, s100, 0xc000
	v_lshl_add_u64 v[106:107], v[254:255], 0, s[16:17]
	global_load_lds_dwordx4 v[106:107], off
	s_mov_b64 s[16:17], 0xb10080
	s_add_u32 m0, s100, 0xd000
	v_lshl_add_u64 v[106:107], v[254:255], 0, s[16:17]
	global_load_lds_dwordx4 v[106:107], off
	ds_read_b128 v[232:235], v163 offset:32768
	s_waitcnt lgkmcnt(2)
	v_mfma_f32_32x32x16_bf16 v[80:95], v[224:227], v[244:247], v[80:95]
	v_mfma_f32_32x32x16_bf16 v[64:79], v[224:227], v[248:251], v[64:79]
	s_mov_b64 s[16:17], 0xb20080
	s_add_u32 m0, s100, 0xe000
	v_lshl_add_u64 v[106:107], v[254:255], 0, s[16:17]
	global_load_lds_dwordx4 v[106:107], off
	s_mov_b64 s[16:17], 0xb30080
	s_add_u32 m0, s100, 0xf000
	v_lshl_add_u64 v[106:107], v[254:255], 0, s[16:17]
	global_load_lds_dwordx4 v[106:107], off
	v_lshl_add_u64 v[254:255], v[254:255], 0, s[0:1]
	ds_read_b128 v[236:239], v172
	ds_read_b128 v[240:243], v172 offset:4096
	ds_read_b128 v[224:227], v164 offset:24576
	s_waitcnt lgkmcnt(4)
	v_mfma_f32_32x32x16_bf16 v[48:63], v[228:231], v[244:247], v[48:63]
	v_mfma_f32_32x32x16_bf16 v[32:47], v[228:231], v[248:251], v[32:47]
	ds_read_b128 v[228:231], v164 offset:28672
	s_waitcnt lgkmcnt(4)
	v_mfma_f32_32x32x16_bf16 v[16:31], v[232:235], v[244:247], v[16:31]
	v_mfma_f32_32x32x16_bf16 v[0:15], v[232:235], v[248:251], v[0:15]
	ds_read_b128 v[232:235], v164 offset:32768
	s_waitcnt lgkmcnt(2)
	v_mfma_f32_32x32x16_bf16 v[80:95], v[224:227], v[236:239], v[80:95]
	v_mfma_f32_32x32x16_bf16 v[64:79], v[224:227], v[240:243], v[64:79]
	ds_read_b128 v[244:247], v173
	ds_read_b128 v[248:251], v173 offset:4096
	ds_read_b128 v[224:227], v165 offset:24576
	s_waitcnt lgkmcnt(4)
	v_mfma_f32_32x32x16_bf16 v[48:63], v[228:231], v[236:239], v[48:63]
	v_mfma_f32_32x32x16_bf16 v[32:47], v[228:231], v[240:243], v[32:47]
	ds_read_b128 v[228:231], v165 offset:28672
	s_waitcnt lgkmcnt(4)
	v_mfma_f32_32x32x16_bf16 v[16:31], v[232:235], v[236:239], v[16:31]
	v_mfma_f32_32x32x16_bf16 v[0:15], v[232:235], v[240:243], v[0:15]
	ds_read_b128 v[232:235], v165 offset:32768
	s_waitcnt lgkmcnt(2)
	v_mfma_f32_32x32x16_bf16 v[80:95], v[224:227], v[244:247], v[80:95]
	v_mfma_f32_32x32x16_bf16 v[64:79], v[224:227], v[248:251], v[64:79]
	s_waitcnt lgkmcnt(0)
	s_waitcnt vmcnt(0)
	s_barrier
	s_add_u32 m0, s100, 0x6000
	v_lshl_add_u64 v[106:107], v[252:253], 0, s[96:97]
	global_load_lds_dwordx4 v[106:107], off
	s_add_u32 m0, s100, 0x7000
	v_lshl_add_u64 v[106:107], v[252:253], 0, s[50:51]
	global_load_lds_dwordx4 v[106:107], off
	ds_read_b128 v[236:239], v166 offset:49152
	ds_read_b128 v[240:243], v166 offset:53248
	ds_read_b128 v[224:227], v162
	v_mfma_f32_32x32x16_bf16 v[48:63], v[228:231], v[244:247], v[48:63]
	v_mfma_f32_32x32x16_bf16 v[32:47], v[228:231], v[248:251], v[32:47]
	ds_read_b128 v[228:231], v162 offset:4096
	v_mfma_f32_32x32x16_bf16 v[16:31], v[232:235], v[244:247], v[16:31]
	v_mfma_f32_32x32x16_bf16 v[0:15], v[232:235], v[248:251], v[0:15]
	s_add_u32 s101, s101, 2
	s_branch .Lgb_loop

; template <int EPI, int MI>
; DI void gemm_tile(const GemmDesc& g, int tm, int tn, char* smem) {
;     ...
;   const int rowA = wm * (32 * MI) + r, rowB = wn * 64 + r;
;   const int hk = hh ^ ((r & 7) ^ ((r >> 3) & 3));
;     ...
;   G_GLDS(0, 0);
;   asm volatile("s_waitcnt vmcnt(0)" ::: "memory");
;   __syncthreads();
;   for (int kt = 0; kt < nk; kt += 2) {
;     if (kt + 1 < nk) G_GLDS(kt + 1, 1);
;     G_COMPUTE(0);
;     asm volatile("s_waitcnt vmcnt(0)" ::: "memory");
;     __syncthreads();
;     if (kt + 1 < nk) {
;       if (kt + 2 < nk) G_GLDS(kt + 2, 0);
;       G_COMPUTE(1);
;       asm volatile("s_waitcnt vmcnt(0)" ::: "memory");
;       __syncthreads();
;     }
;   }
.Lgf_loop:
	ds_read_b128 v[248:251], v98 offset:32768
	ds_read_b128 v[252:255], v98 offset:36864
	ds_read_b128 v[232:235], v93
	s_waitcnt lgkmcnt(4)
	v_mfma_f32_32x32x16_bf16 v[48:63], v[224:227], v[240:243], v[48:63]
	v_mfma_f32_32x32x16_bf16 v[32:47], v[224:227], v[244:247], v[32:47]
	s_mov_b64 s[4:5], 0x58ca080
	s_add_u32 m0, s100, 0x6000
	v_lshl_add_u64 v[102:103], v[104:105], 0, s[4:5]
	global_load_lds_dwordx4 v[102:103], off
	s_mov_b64 s[4:5], 0x58f6080
	s_add_u32 m0, s100, 0x7000
	v_lshl_add_u64 v[102:103], v[104:105], 0, s[4:5]
	global_load_lds_dwordx4 v[102:103], off
	v_lshl_add_u64 v[104:105], v[104:105], 0, s[46:47]
	ds_read_b128 v[236:239], v93 offset:4096
	s_waitcnt lgkmcnt(4)
	v_mfma_f32_32x32x16_bf16 v[16:31], v[228:231], v[240:243], v[16:31]
	v_mfma_f32_32x32x16_bf16 v[0:15], v[228:231], v[244:247], v[0:15]
	s_mov_b64 s[4:5], 0x1b80080
	s_add_u32 m0, s100, 0xc000
	v_lshl_add_u64 v[102:103], v[106:107], 0, s[4:5]
	global_load_lds_dwordx4 v[102:103], off
	s_mov_b64 s[4:5], 0x1bac080
	s_add_u32 m0, s100, 0xd000
	v_lshl_add_u64 v[102:103], v[106:107], 0, s[4:5]
	global_load_lds_dwordx4 v[102:103], off
	ds_read_b128 v[240:243], v99 offset:32768
	ds_read_b128 v[244:247], v99 offset:36864
	ds_read_b128 v[224:227], v94
	s_waitcnt lgkmcnt(4)
	v_mfma_f32_32x32x16_bf16 v[48:63], v[232:235], v[248:251], v[48:63]
	v_mfma_f32_32x32x16_bf16 v[32:47], v[232:235], v[252:255], v[32:47]
	s_mov_b64 s[4:5], 0x1bd8080
	s_add_u32 m0, s100, 0xe000
	v_lshl_add_u64 v[102:103], v[106:107], 0, s[4:5]
	global_load_lds_dwordx4 v[102:103], off
	s_mov_b64 s[4:5], 0x1c04080
	s_add_u32 m0, s100, 0xf000
	v_lshl_add_u64 v[102:103], v[106:107], 0, s[4:5]
	global_load_lds_dwordx4 v[102:103], off
	v_lshl_add_u64 v[106:107], v[106:107], 0, s[46:47]
	ds_read_b128 v[228:231], v94 offset:4096
	s_waitcnt lgkmcnt(4)
	v_mfma_f32_32x32x16_bf16 v[16:31], v[236:239], v[248:251], v[16:31]
	v_mfma_f32_32x32x16_bf16 v[0:15], v[236:239], v[252:255], v[0:15]
	ds_read_b128 v[248:251], v100 offset:32768
	ds_read_b128 v[252:255], v100 offset:36864
	ds_read_b128 v[232:235], v95
	s_waitcnt lgkmcnt(4)
	v_mfma_f32_32x32x16_bf16 v[48:63], v[224:227], v[240:243], v[48:63]
	v_mfma_f32_32x32x16_bf16 v[32:47], v[224:227], v[244:247], v[32:47]
	ds_read_b128 v[236:239], v95 offset:4096
	s_waitcnt lgkmcnt(4)
	v_mfma_f32_32x32x16_bf16 v[16:31], v[228:231], v[240:243], v[16:31]
	v_mfma_f32_32x32x16_bf16 v[0:15], v[228:231], v[244:247], v[0:15]
	s_waitcnt lgkmcnt(0)
	s_waitcnt vmcnt(0)
	s_barrier
	s_cmp_eq_u32 s101, 42
	s_cbranch_scc1 .Lgf_noearly
	s_mov_b64 s[4:5], 0x5872080
	s_mov_b32 m0, s100
	v_lshl_add_u64 v[102:103], v[104:105], 0, s[4:5]
	global_load_lds_dwordx4 v[102:103], off
	s_mov_b64 s[4:5], 0x589e080
	s_add_u32 m0, s100, 0x1000
	v_lshl_add_u64 v[102:103], v[104:105], 0, s[4:5]
	global_load_lds_dwordx4 v[102:103], off
.Lgf_noearly:
	ds_read_b128 v[240:243], v97 offset:49152
	ds_read_b128 v[244:247], v97 offset:53248
	ds_read_b128 v[224:227], v92 offset:16384
	v_mfma_f32_32x32x16_bf16 v[48:63], v[232:235], v[248:251], v[48:63]
	v_mfma_f32_32x32x16_bf16 v[32:47], v[232:235], v[252:255], v[32:47]
	ds_read_b128 v[228:231], v92 offset:20480
	v_mfma_f32_32x32x16_bf16 v[16:31], v[236:239], v[248:251], v[16:31]
	v_mfma_f32_32x32x16_bf16 v[0:15], v[236:239], v[252:255], v[0:15]
	s_cmp_eq_u32 s101, 42
	s_cbranch_scc1 .Lgf_last
	ds_read_b128 v[248:251], v98 offset:49152
	ds_read_b128 v[252:255], v98 offset:53248
	ds_read_b128 v[232:235], v93 offset:16384
	s_waitcnt lgkmcnt(4)
	v_mfma_f32_32x32x16_bf16 v[48:63], v[224:227], v[240:243], v[48:63]
	v_mfma_f32_32x32x16_bf16 v[32:47], v[224:227], v[244:247], v[32:47]
	s_mov_b64 s[4:5], 0x58ca080
	s_add_u32 m0, s100, 0x2000
	v_lshl_add_u64 v[102:103], v[104:105], 0, s[4:5]
	global_load_lds_dwordx4 v[102:103], off
	s_mov_b64 s[4:5], 0x58f6080
	s_add_u32 m0, s100, 0x3000
	v_lshl_add_u64 v[102:103], v[104:105], 0, s[4:5]
	global_load_lds_dwordx4 v[102:103], off
	v_lshl_add_u64 v[104:105], v[104:105], 0, s[46:47]
	ds_read_b128 v[236:239], v93 offset:20480
	s_waitcnt lgkmcnt(4)
	v_mfma_f32_32x32x16_bf16 v[16:31], v[228:231], v[240:243], v[16:31]
	v_mfma_f32_32x32x16_bf16 v[0:15], v[228:231], v[244:247], v[0:15]
	s_mov_b64 s[4:5], 0x1b80080
	s_add_u32 m0, s100, 0x8000
	v_lshl_add_u64 v[102:103], v[106:107], 0, s[4:5]
	global_load_lds_dwordx4 v[102:103], off
	s_mov_b64 s[4:5], 0x1bac080
	s_add_u32 m0, s100, 0x9000
	v_lshl_add_u64 v[102:103], v[106:107], 0, s[4:5]
	global_load_lds_dwordx4 v[102:103], off
	ds_read_b128 v[240:243], v99 offset:49152
	ds_read_b128 v[244:247], v99 offset:53248
	ds_read_b128 v[224:227], v94 offset:16384
	s_waitcnt lgkmcnt(4)
	v_mfma_f32_32x32x16_bf16 v[48:63], v[232:235], v[248:251], v[48:63]
	v_mfma_f32_32x32x16_bf16 v[32:47], v[232:235], v[252:255], v[32:47]
	s_mov_b64 s[4:5], 0x1bd8080
	s_add_u32 m0, s100, 0xa000
	v_lshl_add_u64 v[102:103], v[106:107], 0, s[4:5]
	global_load_lds_dwordx4 v[102:103], off
	s_mov_b64 s[4:5], 0x1c04080
	s_add_u32 m0, s100, 0xb000
	v_lshl_add_u64 v[102:103], v[106:107], 0, s[4:5]
	global_load_lds_dwordx4 v[102:103], off
	v_lshl_add_u64 v[106:107], v[106:107], 0, s[46:47]
	ds_read_b128 v[228:231], v94 offset:20480
	s_waitcnt lgkmcnt(4)
	v_mfma_f32_32x32x16_bf16 v[16:31], v[236:239], v[248:251], v[16:31]
	v_mfma_f32_32x32x16_bf16 v[0:15], v[236:239], v[252:255], v[0:15]
	ds_read_b128 v[248:251], v100 offset:49152
	ds_read_b128 v[252:255], v100 offset:53248
	ds_read_b128 v[232:235], v95 offset:16384
	s_waitcnt lgkmcnt(4)
	v_mfma_f32_32x32x16_bf16 v[48:63], v[224:227], v[240:243], v[48:63]
	v_mfma_f32_32x32x16_bf16 v[32:47], v[224:227], v[244:247], v[32:47]
	ds_read_b128 v[236:239], v95 offset:20480
	s_waitcnt lgkmcnt(4)
	v_mfma_f32_32x32x16_bf16 v[16:31], v[228:231], v[240:243], v[16:31]
	v_mfma_f32_32x32x16_bf16 v[0:15], v[228:231], v[244:247], v[0:15]
	s_waitcnt lgkmcnt(0)
	s_waitcnt vmcnt(0)
	s_barrier
	s_mov_b64 s[4:5], 0x5872080
	s_add_u32 m0, s100, 0x4000
	v_lshl_add_u64 v[102:103], v[104:105], 0, s[4:5]
	global_load_lds_dwordx4 v[102:103], off
	s_mov_b64 s[4:5], 0x589e080
	s_add_u32 m0, s100, 0x5000
	v_lshl_add_u64 v[102:103], v[104:105], 0, s[4:5]
	global_load_lds_dwordx4 v[102:103], off
	ds_read_b128 v[240:243], v97 offset:32768
	ds_read_b128 v[244:247], v97 offset:36864
	ds_read_b128 v[224:227], v92
	v_mfma_f32_32x32x16_bf16 v[48:63], v[232:235], v[248:251], v[48:63]
	v_mfma_f32_32x32x16_bf16 v[32:47], v[232:235], v[252:255], v[32:47]
	ds_read_b128 v[228:231], v92 offset:4096
	v_mfma_f32_32x32x16_bf16 v[16:31], v[236:239], v[248:251], v[16:31]
	v_mfma_f32_32x32x16_bf16 v[0:15], v[236:239], v[252:255], v[0:15]
	s_add_u32 s101, s101, 2
	s_branch .Lgf_loop

; template <int EPI, int MI>
; DI void gemm_tile(const GemmDesc& g, int tm, int tn, char* smem) {
;     ...
;   const int rowA = wm * (32 * MI) + r, rowB = wn * 64 + r;
;   const int hk = hh ^ ((r & 7) ^ ((r >> 3) & 3));
;     ...
;   G_GLDS(0, 0);
;   asm volatile("s_waitcnt vmcnt(0)" ::: "memory");
;   __syncthreads();
;   for (int kt = 0; kt < nk; kt += 2) {
;     if (kt + 1 < nk) G_GLDS(kt + 1, 1);
;     G_COMPUTE(0);
;     asm volatile("s_waitcnt vmcnt(0)" ::: "memory");
;     __syncthreads();
;     if (kt + 1 < nk) {
;       if (kt + 2 < nk) G_GLDS(kt + 2, 0);
;       G_COMPUTE(1);
;       asm volatile("s_waitcnt vmcnt(0)" ::: "memory");
;       __syncthreads();
;     }
;   }
.Lge_loop:
	ds_read_b128 v[232:235], v162 offset:8192
	s_waitcnt lgkmcnt(2)
	v_mfma_f32_32x32x16_bf16 v[80:95], v[224:227], v[236:239], v[80:95]
	v_mfma_f32_32x32x16_bf16 v[64:79], v[224:227], v[240:243], v[64:79]
	s_mov_b64 s[16:17], 0x58ca080
	s_add_u32 m0, s100, 0x8000
	v_lshl_add_u64 v[106:107], v[252:253], 0, s[16:17]
	global_load_lds_dwordx4 v[106:107], off
	s_mov_b64 s[16:17], 0x58f6080
	s_add_u32 m0, s100, 0x9000
	v_lshl_add_u64 v[106:107], v[252:253], 0, s[16:17]
	global_load_lds_dwordx4 v[106:107], off
	ds_read_b128 v[244:247], v167 offset:49152
	ds_read_b128 v[248:251], v167 offset:53248
	ds_read_b128 v[224:227], v163
	s_waitcnt lgkmcnt(4)
	v_mfma_f32_32x32x16_bf16 v[48:63], v[228:231], v[236:239], v[48:63]
	v_mfma_f32_32x32x16_bf16 v[32:47], v[228:231], v[240:243], v[32:47]
	s_mov_b64 s[16:17], 0x5922080
	s_add_u32 m0, s100, 0xa000
	v_lshl_add_u64 v[106:107], v[252:253], 0, s[16:17]
	global_load_lds_dwordx4 v[106:107], off
	s_mov_b64 s[16:17], 0x594e080
	s_add_u32 m0, s100, 0xb000
	v_lshl_add_u64 v[106:107], v[252:253], 0, s[16:17]
	global_load_lds_dwordx4 v[106:107], off
	v_lshl_add_u64 v[252:253], v[252:253], 0, s[4:5]
	ds_read_b128 v[228:231], v163 offset:4096
	s_waitcnt lgkmcnt(4)
	v_mfma_f32_32x32x16_bf16 v[16:31], v[232:235], v[236:239], v[16:31]
	v_mfma_f32_32x32x16_bf16 v[0:15], v[232:235], v[240:243], v[0:15]
	s_mov_b64 s[16:17], 0x1b80080
	s_add_u32 m0, s100, 0x10000
	v_lshl_add_u64 v[106:107], v[254:255], 0, s[16:17]
	global_load_lds_dwordx4 v[106:107], off
	s_mov_b64 s[16:17], 0x1bac080
	s_add_u32 m0, s100, 0x11000
	v_lshl_add_u64 v[106:107], v[254:255], 0, s[16:17]
	global_load_lds_dwordx4 v[106:107], off
	ds_read_b128 v[232:235], v163 offset:8192
	s_waitcnt lgkmcnt(2)
	v_mfma_f32_32x32x16_bf16 v[80:95], v[224:227], v[244:247], v[80:95]
	v_mfma_f32_32x32x16_bf16 v[64:79], v[224:227], v[248:251], v[64:79]
	s_mov_b64 s[16:17], 0x1bd8080
	s_add_u32 m0, s100, 0x12000
	v_lshl_add_u64 v[106:107], v[254:255], 0, s[16:17]
	global_load_lds_dwordx4 v[106:107], off
	s_mov_b64 s[16:17], 0x1c04080
	s_add_u32 m0, s100, 0x13000
	v_lshl_add_u64 v[106:107], v[254:255], 0, s[16:17]
	global_load_lds_dwordx4 v[106:107], off
	v_lshl_add_u64 v[254:255], v[254:255], 0, s[4:5]
	ds_read_b128 v[236:239], v168 offset:49152
	ds_read_b128 v[240:243], v168 offset:53248
	ds_read_b128 v[224:227], v164
	s_waitcnt lgkmcnt(4)
	v_mfma_f32_32x32x16_bf16 v[48:63], v[228:231], v[244:247], v[48:63]
	v_mfma_f32_32x32x16_bf16 v[32:47], v[228:231], v[248:251], v[32:47]
	ds_read_b128 v[228:231], v164 offset:4096
	s_waitcnt lgkmcnt(4)
	v_mfma_f32_32x32x16_bf16 v[16:31], v[232:235], v[244:247], v[16:31]
	v_mfma_f32_32x32x16_bf16 v[0:15], v[232:235], v[248:251], v[0:15]
	ds_read_b128 v[232:235], v164 offset:8192
	s_waitcnt lgkmcnt(2)
	v_mfma_f32_32x32x16_bf16 v[80:95], v[224:227], v[236:239], v[80:95]
	v_mfma_f32_32x32x16_bf16 v[64:79], v[224:227], v[240:243], v[64:79]
	ds_read_b128 v[244:247], v169 offset:49152
	ds_read_b128 v[248:251], v169 offset:53248
	ds_read_b128 v[224:227], v165
	s_waitcnt lgkmcnt(4)
	v_mfma_f32_32x32x16_bf16 v[48:63], v[228:231], v[236:239], v[48:63]
	v_mfma_f32_32x32x16_bf16 v[32:47], v[228:231], v[240:243], v[32:47]
	ds_read_b128 v[228:231], v165 offset:4096
	s_waitcnt lgkmcnt(4)
	v_mfma_f32_32x32x16_bf16 v[16:31], v[232:235], v[236:239], v[16:31]
	v_mfma_f32_32x32x16_bf16 v[0:15], v[232:235], v[240:243], v[0:15]
	ds_read_b128 v[232:235], v165 offset:8192
	s_waitcnt lgkmcnt(2)
	v_mfma_f32_32x32x16_bf16 v[80:95], v[224:227], v[244:247], v[80:95]
	v_mfma_f32_32x32x16_bf16 v[64:79], v[224:227], v[248:251], v[64:79]
	s_waitcnt lgkmcnt(0)
	s_waitcnt vmcnt(0)
	s_barrier
	s_cmp_eq_u32 s15, 42
	s_cbranch_scc1 .Lge_noearly
	s_mov_b64 s[16:17], 0x5872080
	s_mov_b32 m0, s100
	v_lshl_add_u64 v[106:107], v[252:253], 0, s[16:17]
	global_load_lds_dwordx4 v[106:107], off
	s_mov_b64 s[16:17], 0x589e080
	s_add_u32 m0, s100, 0x1000
	v_lshl_add_u64 v[106:107], v[252:253], 0, s[16:17]
	global_load_lds_dwordx4 v[106:107], off
; template <int EPI, int MI>
; DI void gemm_tile(const GemmDesc& g, int tm, int tn, char* smem) {
;     ...
;   const int rowA = wm * (32 * MI) + r, rowB = wn * 64 + r;
;   const int hk = hh ^ ((r & 7) ^ ((r >> 3) & 3));
;     ...
;   G_GLDS(0, 0);
;   asm volatile("s_waitcnt vmcnt(0)" ::: "memory");
;   __syncthreads();
;   for (int kt = 0; kt < nk; kt += 2) {
;     if (kt + 1 < nk) G_GLDS(kt + 1, 1);
;     G_COMPUTE(0);
;     asm volatile("s_waitcnt vmcnt(0)" ::: "memory");
;     __syncthreads();
;     if (kt + 1 < nk) {
;       if (kt + 2 < nk) G_GLDS(kt + 2, 0);
;       G_COMPUTE(1);
;       asm volatile("s_waitcnt vmcnt(0)" ::: "memory");
;       __syncthreads();
;     }
;   }
.Lge_noearly:
	ds_read_b128 v[236:239], v170
	ds_read_b128 v[240:243], v170 offset:4096
	ds_read_b128 v[224:227], v162 offset:24576
	v_mfma_f32_32x32x16_bf16 v[48:63], v[228:231], v[244:247], v[48:63]
	v_mfma_f32_32x32x16_bf16 v[32:47], v[228:231], v[248:251], v[32:47]
	ds_read_b128 v[228:231], v162 offset:28672
	v_mfma_f32_32x32x16_bf16 v[16:31], v[232:235], v[244:247], v[16:31]
	v_mfma_f32_32x32x16_bf16 v[0:15], v[232:235], v[248:251], v[0:15]
	s_cmp_eq_u32 s15, 42
	s_cbranch_scc1 .Lge_last
	ds_read_b128 v[232:235], v162 offset:32768
	s_waitcnt lgkmcnt(2)
	v_mfma_f32_32x32x16_bf16 v[80:95], v[224:227], v[236:239], v[80:95]
	v_mfma_f32_32x32x16_bf16 v[64:79], v[224:227], v[240:243], v[64:79]
	s_mov_b64 s[16:17], 0x58ca080
	s_add_u32 m0, s100, 0x2000
	v_lshl_add_u64 v[106:107], v[252:253], 0, s[16:17]
	global_load_lds_dwordx4 v[106:107], off
	s_mov_b64 s[16:17], 0x58f6080
	s_add_u32 m0, s100, 0x3000
	v_lshl_add_u64 v[106:107], v[252:253], 0, s[16:17]
	global_load_lds_dwordx4 v[106:107], off
	ds_read_b128 v[244:247], v171
	ds_read_b128 v[248:251], v171 offset:4096
	ds_read_b128 v[224:227], v163 offset:24576
	s_waitcnt lgkmcnt(4)
	v_mfma_f32_32x32x16_bf16 v[48:63], v[228:231], v[236:239], v[48:63]
	v_mfma_f32_32x32x16_bf16 v[32:47], v[228:231], v[240:243], v[32:47]
	s_mov_b64 s[16:17], 0x5922080
	s_add_u32 m0, s100, 0x4000
	v_lshl_add_u64 v[106:107], v[252:253], 0, s[16:17]
	global_load_lds_dwordx4 v[106:107], off
	s_mov_b64 s[16:17], 0x594e080
	s_add_u32 m0, s100, 0x5000
	v_lshl_add_u64 v[106:107], v[252:253], 0, s[16:17]
	global_load_lds_dwordx4 v[106:107], off
	v_lshl_add_u64 v[252:253], v[252:253], 0, s[4:5]
	ds_read_b128 v[228:231], v163 offset:28672
	s_waitcnt lgkmcnt(4)
	v_mfma_f32_32x32x16_bf16 v[16:31], v[232:235], v[236:239], v[16:31]
	v_mfma_f32_32x32x16_bf16 v[0:15], v[232:235], v[240:243], v[0:15]
	s_mov_b64 s[16:17], 0x1b80080
	s_add_u32 m0, s100, 0xc000
	v_lshl_add_u64 v[106:107], v[254:255], 0, s[16:17]
	global_load_lds_dwordx4 v[106:107], off
	s_mov_b64 s[16:17], 0x1bac080
	s_add_u32 m0, s100, 0xd000
	v_lshl_add_u64 v[106:107], v[254:255], 0, s[16:17]
	global_load_lds_dwordx4 v[106:107], off
	ds_read_b128 v[232:235], v163 offset:32768
	s_waitcnt lgkmcnt(2)
	v_mfma_f32_32x32x16_bf16 v[80:95], v[224:227], v[244:247], v[80:95]
	v_mfma_f32_32x32x16_bf16 v[64:79], v[224:227], v[248:251], v[64:79]
	s_mov_b64 s[16:17], 0x1bd8080
	s_add_u32 m0, s100, 0xe000
	v_lshl_add_u64 v[106:107], v[254:255], 0, s[16:17]
	global_load_lds_dwordx4 v[106:107], off
	s_mov_b64 s[16:17], 0x1c04080
	s_add_u32 m0, s100, 0xf000
	v_lshl_add_u64 v[106:107], v[254:255], 0, s[16:17]
	global_load_lds_dwordx4 v[106:107], off
	v_lshl_add_u64 v[254:255], v[254:255], 0, s[4:5]
	ds_read_b128 v[236:239], v172
	ds_read_b128 v[240:243], v172 offset:4096
	ds_read_b128 v[224:227], v164 offset:24576
	s_waitcnt lgkmcnt(4)
	v_mfma_f32_32x32x16_bf16 v[48:63], v[228:231], v[244:247], v[48:63]
	v_mfma_f32_32x32x16_bf16 v[32:47], v[228:231], v[248:251], v[32:47]
	ds_read_b128 v[228:231], v164 offset:28672
	s_waitcnt lgkmcnt(4)
	v_mfma_f32_32x32x16_bf16 v[16:31], v[232:235], v[244:247], v[16:31]
	v_mfma_f32_32x32x16_bf16 v[0:15], v[232:235], v[248:251], v[0:15]
	ds_read_b128 v[232:235], v164 offset:32768
	s_waitcnt lgkmcnt(2)
	v_mfma_f32_32x32x16_bf16 v[80:95], v[224:227], v[236:239], v[80:95]
	v_mfma_f32_32x32x16_bf16 v[64:79], v[224:227], v[240:243], v[64:79]
	ds_read_b128 v[244:247], v173
	ds_read_b128 v[248:251], v173 offset:4096
	ds_read_b128 v[224:227], v165 offset:24576
	s_waitcnt lgkmcnt(4)
	v_mfma_f32_32x32x16_bf16 v[48:63], v[228:231], v[236:239], v[48:63]
	v_mfma_f32_32x32x16_bf16 v[32:47], v[228:231], v[240:243], v[32:47]
	ds_read_b128 v[228:231], v165 offset:28672
	s_waitcnt lgkmcnt(4)
	v_mfma_f32_32x32x16_bf16 v[16:31], v[232:235], v[236:239], v[16:31]
	v_mfma_f32_32x32x16_bf16 v[0:15], v[232:235], v[240:243], v[0:15]
	ds_read_b128 v[232:235], v165 offset:32768
	s_waitcnt lgkmcnt(2)
	v_mfma_f32_32x32x16_bf16 v[80:95], v[224:227], v[244:247], v[80:95]
	v_mfma_f32_32x32x16_bf16 v[64:79], v[224:227], v[248:251], v[64:79]
	s_waitcnt lgkmcnt(0)
	s_waitcnt vmcnt(0)
	s_barrier
	s_mov_b64 s[16:17], 0x5872080
	s_add_u32 m0, s100, 0x6000
	v_lshl_add_u64 v[106:107], v[252:253], 0, s[16:17]
	global_load_lds_dwordx4 v[106:107], off
	s_mov_b64 s[16:17], 0x589e080
	s_add_u32 m0, s100, 0x7000
	v_lshl_add_u64 v[106:107], v[252:253], 0, s[16:17]
	global_load_lds_dwordx4 v[106:107], off
	ds_read_b128 v[236:239], v166 offset:49152
	ds_read_b128 v[240:243], v166 offset:53248
	ds_read_b128 v[224:227], v162
	v_mfma_f32_32x32x16_bf16 v[48:63], v[228:231], v[244:247], v[48:63]
	v_mfma_f32_32x32x16_bf16 v[32:47], v[228:231], v[248:251], v[32:47]
	ds_read_b128 v[228:231], v162 offset:4096
	v_mfma_f32_32x32x16_bf16 v[16:31], v[232:235], v[244:247], v[16:31]
	v_mfma_f32_32x32x16_bf16 v[0:15], v[232:235], v[248:251], v[0:15]
	s_add_u32 s15, s15, 2
	s_branch .Lge_loop
